# XCD-local barriers: workgroups poll the XCC arrival counter itself (release one round trip after the last arrival, no leader hop); last arriver still bumps XGEN for bookkeeping; placement flag compute
# baseline (speedup 1.0000x reference)
; __device__ __forceinline__ unsigned xb_ld(unsigned* p)              { return __hip_atomic_load(p, __ATOMIC_RELAXED, __HIP_MEMORY_SCOPE_AGENT); }
; __device__ __forceinline__ unsigned xb_add(unsigned* p, unsigned v) { return __hip_atomic_fetch_add(p, v, __ATOMIC_RELAXED, __HIP_MEMORY_SCOPE_AGENT); }
; #define XB_SPIN(cond, bar) do { unsigned _sp = 0; while (cond) { __builtin_amdgcn_s_sleep(1); \
;     if ((++_sp & 255u) == 0u) { if (xb_ld(&(bar)[XB_TMO])) break; if (_sp > XB_SPIN_CAP) { atomicAdd(&(bar)[XB_TMO], 1u); break; } } } } while (0)
; __device__ __forceinline__ void xcd_barrier(const XcdBarrier& b) {
;     ...
;         unsigned nloc = b.st[0], nx = b.st[1];
;         if (nloc == 0u) { xcd_barrier_complete(bar, b.x, nloc, nx); b.st[0] = nloc; b.st[1] = nx; }
;         const unsigned old = xb_add(&bar[XB_XSUB(b.x)], 1u);
;         const unsigned gen = old / nloc;
;         if (old + 1u == (gen + 1u) * nloc) {
;             __builtin_amdgcn_fence(__ATOMIC_RELEASE, "agent");
;             asm volatile("s_waitcnt vmcnt(0)" ::: "memory");
;             const unsigned og = xb_add(&bar[XB_TOP], 1u);
;             const unsigned tg = og / nx;
;             if (og + 1u == (tg + 1u) * nx) xb_add(&bar[XB_TOPGEN], 1u);
;             else XB_SPIN(xb_ld(&bar[XB_TOPGEN]) == tg, bar);
;             __builtin_amdgcn_fence(__ATOMIC_ACQUIRE, "agent");
;             xb_add(&bar[XB_XGEN(b.x)], 1u);
;             asm volatile("s_waitcnt vmcnt(0)" ::: "memory");
;         } else {
;             XB_SPIN(xb_ld(&bar[XB_XGEN(b.x)]) == gen, bar);
.LBB0_721:
	s_or_b64 exec, exec, s[4:5]
	v_cvt_f32_u32_e32 v4, v2
	s_waitcnt vmcnt(0)
	v_readfirstlane_b32 s4, v3
	v_sub_u32_e32 v3, 0, v2
	v_rcp_iflag_f32_e32 v4, v4
	v_add_u32_e32 v5, s4, v1
	v_mul_f32_e32 v4, 0x4f7ffffe, v4
	v_cvt_u32_f32_e32 v4, v4
	v_mul_lo_u32 v1, v3, v4
	v_mul_hi_u32 v1, v4, v1
	v_add_u32_e32 v1, v4, v1
	v_mul_hi_u32 v1, v5, v1
	v_mul_lo_u32 v3, v1, v2
	v_sub_u32_e32 v3, v5, v3
	v_add_u32_e32 v4, 1, v1
	v_cmp_ge_u32_e32 vcc, v3, v2
	s_nop 1
	v_cndmask_b32_e32 v1, v1, v4, vcc
	v_sub_u32_e32 v4, v3, v2
	v_cndmask_b32_e32 v3, v3, v4, vcc
	v_add_u32_e32 v4, 1, v1
	v_cmp_ge_u32_e32 vcc, v3, v2
	v_add_u32_e32 v3, 1, v5
	s_nop 0
	v_cndmask_b32_e32 v1, v1, v4, vcc
	v_mul_lo_u32 v4, v2, v1
	v_add_u32_e32 v2, v4, v2
	s_add_i32 s100, s28, -2
	s_and_b32 s101, s100, 7
	s_cmp_lt_u32 s100, 31
	s_cselect_b32 s100, 1, 0
	s_lshl_b32 s101, 1, s101
	s_and_b32 s101, s101, 0x73
	s_cmp_lg_u32 s101, 0
	s_cselect_b32 s101, 1, 0
	s_and_b32 s101, s100, s101
	s_cmp_eq_u32 s101, 0
	s_cbranch_scc1 .Lbar_mode_done
	v_mov_b32_e32 v6, 0x20008
	ds_read_b32 v7, v6
	s_waitcnt lgkmcnt(0)
	v_readfirstlane_b32 s100, v7
	s_cmp_lg_u32 s100, 0
	s_cbranch_scc1 .Lbar_have_flag
	v_readlane_b32 s10, v253, 48
	v_readlane_b32 s11, v253, 49
	s_nop 4
	global_load_dword v7, v197, s[10:11] offset:1024 sc1
	global_load_dword v8, v197, s[10:11] offset:1280 sc1
	global_load_dword v9, v197, s[10:11] offset:1536 sc1
	global_load_dword v10, v197, s[10:11] offset:1792 sc1
	global_load_dword v11, v197, s[10:11] offset:2048 sc1
	global_load_dword v12, v197, s[10:11] offset:2304 sc1
	global_load_dword v13, v197, s[10:11] offset:2560 sc1
	global_load_dword v14, v197, s[10:11] offset:2816 sc1
	s_waitcnt vmcnt(0)
	v_add_u32_e32 v15, -1, v7
	v_and_b32_e32 v15, v15, v7
	v_add_u32_e32 v16, -1, v8
	v_and_or_b32 v15, v16, v8, v15
	v_add_u32_e32 v16, -1, v9
	v_and_or_b32 v15, v16, v9, v15
	v_add_u32_e32 v16, -1, v10
	v_and_or_b32 v15, v16, v10, v15
	v_add_u32_e32 v16, -1, v11
	v_and_or_b32 v15, v16, v11, v15
	v_add_u32_e32 v16, -1, v12
	v_and_or_b32 v15, v16, v12, v15
	v_add_u32_e32 v16, -1, v13
	v_and_or_b32 v15, v16, v13, v15
	v_add_u32_e32 v16, -1, v14
	v_and_or_b32 v15, v16, v14, v15
	v_min_u32_e32 v16, v7, v8
	v_min3_u32 v16, v16, v9, v10
	v_min3_u32 v16, v16, v11, v12
	v_min3_u32 v16, v16, v13, v14
	v_cmp_eq_u32_e32 vcc, 0, v15
	v_mov_b32_e32 v7, 2
	s_nop 0
	v_cndmask_b32_e64 v7, v7, 1, vcc
	v_cmp_eq_u32_e32 vcc, 0, v16
	s_nop 1
	v_cndmask_b32_e64 v7, v7, 2, vcc
	ds_write_b32 v6, v7
	s_nop 0
	v_readfirstlane_b32 s100, v7
.Lbar_have_flag:
	s_cmp_eq_u32 s100, 1
	s_cselect_b32 s101, 1, 0
.Lbar_mode_done:
	v_cmp_ne_u32_e32 vcc, v3, v2
	s_and_saveexec_b64 s[4:5], vcc
	s_xor_b64 s[4:5], exec, s[4:5]
	s_cbranch_execz .LBB0_735
	v_readlane_b32 s10, v253, 46
	v_readlane_b32 s11, v253, 47
	v_add_u32_e32 v5, 1, v1
	s_cmp_eq_u32 s101, 1
	s_cbranch_scc0 .Lbar_nl_glob
	v_readlane_b32 s10, v253, 44
	v_readlane_b32 s11, v253, 45
	v_mov_b32_e32 v5, v2
.Lbar_nl_glob:
	s_waitcnt lgkmcnt(0)
	s_nop 4
	global_load_dword v0, v197, s[10:11] sc1
	s_waitcnt vmcnt(0)
	v_cmp_lt_u32_e32 vcc, v0, v5
	s_and_saveexec_b64 s[10:11], vcc
	s_cbranch_execz .LBB0_734
	s_mov_b32 s8, 1
	s_mov_b64 s[12:13], 0
	s_branch .LBB0_725

; __device__ __forceinline__ unsigned xb_ld(unsigned* p)              { return __hip_atomic_load(p, __ATOMIC_RELAXED, __HIP_MEMORY_SCOPE_AGENT); }
; __device__ __forceinline__ unsigned xb_add(unsigned* p, unsigned v) { return __hip_atomic_fetch_add(p, v, __ATOMIC_RELAXED, __HIP_MEMORY_SCOPE_AGENT); }
; #define XB_SPIN(cond, bar) do { unsigned _sp = 0; while (cond) { __builtin_amdgcn_s_sleep(1); \
;     if ((++_sp & 255u) == 0u) { if (xb_ld(&(bar)[XB_TMO])) break; if (_sp > XB_SPIN_CAP) { atomicAdd(&(bar)[XB_TMO], 1u); break; } } } } while (0)
; __device__ __forceinline__ void xcd_barrier(const XcdBarrier& b) {
;     ...
;             else XB_SPIN(xb_ld(&bar[XB_TOPGEN]) == tg, bar);
;             __builtin_amdgcn_fence(__ATOMIC_ACQUIRE, "agent");
;             xb_add(&bar[XB_XGEN(b.x)], 1u);
;             asm volatile("s_waitcnt vmcnt(0)" ::: "memory");
;         } else {
;             XB_SPIN(xb_ld(&bar[XB_XGEN(b.x)]) == gen, bar);
.LBB0_729:
	v_readlane_b32 s16, v253, 46
	v_readlane_b32 s17, v253, 47
	s_cmp_eq_u32 s101, 1
	s_cbranch_scc0 .Lbar_poll_glob
	v_readlane_b32 s16, v253, 44
	v_readlane_b32 s17, v253, 45
.Lbar_poll_glob:
	s_add_i32 s8, s8, 1
	s_mov_b64 s[18:19], -1
	s_nop 3
	global_load_dword v0, v197, s[16:17] sc1
	s_waitcnt vmcnt(0)
	v_cmp_ge_u32_e32 vcc, v0, v5
	s_orn2_b64 s[16:17], vcc, exec
	s_branch .LBB0_724

; __device__ __forceinline__ unsigned xb_ld(unsigned* p)              { return __hip_atomic_load(p, __ATOMIC_RELAXED, __HIP_MEMORY_SCOPE_AGENT); }
; __device__ __forceinline__ unsigned xb_add(unsigned* p, unsigned v) { return __hip_atomic_fetch_add(p, v, __ATOMIC_RELAXED, __HIP_MEMORY_SCOPE_AGENT); }
; #define XB_SPIN(cond, bar) do { unsigned _sp = 0; while (cond) { __builtin_amdgcn_s_sleep(1); \
;     if ((++_sp & 255u) == 0u) { if (xb_ld(&(bar)[XB_TMO])) break; if (_sp > XB_SPIN_CAP) { atomicAdd(&(bar)[XB_TMO], 1u); break; } } } } while (0)
; __device__ __forceinline__ void xcd_barrier(const XcdBarrier& b) {
;     ...
;         const unsigned old = xb_add(&bar[XB_XSUB(b.x)], 1u);
;         const unsigned gen = old / nloc;
;         if (old + 1u == (gen + 1u) * nloc) {
;             __builtin_amdgcn_fence(__ATOMIC_RELEASE, "agent");
;             asm volatile("s_waitcnt vmcnt(0)" ::: "memory");
;             const unsigned og = xb_add(&bar[XB_TOP], 1u);
;             const unsigned tg = og / nx;
;             if (og + 1u == (tg + 1u) * nx) xb_add(&bar[XB_TOPGEN], 1u);
;             else XB_SPIN(xb_ld(&bar[XB_TOPGEN]) == tg, bar);
;             __builtin_amdgcn_fence(__ATOMIC_ACQUIRE, "agent");
;             xb_add(&bar[XB_XGEN(b.x)], 1u);
;             asm volatile("s_waitcnt vmcnt(0)" ::: "memory");
;         } else {
.LBB0_735:
	s_andn2_saveexec_b64 s[4:5], s[4:5]
	s_cbranch_execz .LBB0_755
	s_mov_b64 s[4:5], exec
	s_cmp_eq_u32 s101, 1
	s_cbranch_scc0 .Lbar_global
	s_waitcnt lgkmcnt(0)
	s_branch .LBB0_752
